# pass A step 1 loop hand-written: glr row read as (r, r+4) pairs, no register shuffles, dead log range fix-ups dropped, 229 -> 140 instructions per 4 tokens, bit-exact
# speedup vs baseline: 1.0032x; 1.0003x over previous
; #define LAS __attribute__((address_space(3)))
; __device__ __forceinline__ float logsig_f(float z) { return fminf(z, 0.f) - __logf(1.f + __expf(-fabsf(z))); }
; __device__ __forceinline__ void gla_passA(LAS unsigned char* lds, int uidx, const bf16_t* PR, const float* GLRP, const float* w2, const float* gb,
;                                           bf16_t* SUB, float* EB, bf16_t* QT, bf16_t* AM, int tid, int wid, int lane) {
;     ...
;     { float run = 0.f;
; #pragma unroll 4
;       for (int i = 0; i < 16; ++i) { const int t = 16 * tg + i; const LAS f32x4* gr = (const LAS f32x4*)(Gs + t * 16); const f32x4 a0 = gr[0], a1 = gr[1], a2 = gr[2], a3 = gr[3];
;           float z = bias;
;           z += a0.x * wk[0] + a0.y * wk[1] + a0.z * wk[2] + a0.w * wk[3]; z += a1.x * wk[4] + a1.y * wk[5] + a1.z * wk[6] + a1.w * wk[7];
;           z += a2.x * wk[8] + a2.y * wk[9] + a2.z * wk[10] + a2.w * wk[11]; z += a3.x * wk[12] + a3.y * wk[13] + a3.z * wk[14] + a3.w * wk[15];
;           run += logsig_f(z) * (1.f / 16.f); Bc[t * 129 + kcol] = run; }
;       Tt[tg * 128 + kcol] = run; }
;     __syncthreads();
.Lpa_nopf:
.LBB0_352:
	v_add_u32_e32 v254, 0x1d700, v17
	ds_read2_b32 v[20:21], v254 offset0:0 offset1:4
	ds_read2_b32 v[22:23], v254 offset0:1 offset1:5
	ds_read2_b32 v[24:25], v254 offset0:2 offset1:6
	ds_read2_b32 v[26:27], v254 offset0:3 offset1:7
	ds_read2_b32 v[28:29], v254 offset0:8 offset1:12
	ds_read2_b32 v[30:31], v254 offset0:9 offset1:13
	ds_read2_b32 v[52:53], v254 offset0:10 offset1:14
	ds_read2_b32 v[54:55], v254 offset0:11 offset1:15
	ds_read2_b32 v[56:57], v254 offset0:16 offset1:20
	ds_read2_b32 v[58:59], v254 offset0:17 offset1:21
	ds_read2_b32 v[60:61], v254 offset0:18 offset1:22
	ds_read2_b32 v[62:63], v254 offset0:19 offset1:23
	ds_read2_b32 v[64:65], v254 offset0:24 offset1:28
	ds_read2_b32 v[66:67], v254 offset0:25 offset1:29
	ds_read2_b32 v[214:215], v254 offset0:26 offset1:30
	ds_read2_b32 v[252:253], v254 offset0:27 offset1:31
	s_waitcnt lgkmcnt(8)
	v_pk_mul_f32 v[22:23], v[36:37], v[22:23]
	v_pk_mul_f32 v[30:31], v[44:45], v[30:31]
	v_pk_fma_f32 v[22:23], v[34:35], v[20:21], v[22:23]
	v_pk_fma_f32 v[30:31], v[42:43], v[28:29], v[30:31]
	v_pk_fma_f32 v[22:23], v[38:39], v[24:25], v[22:23]
	v_pk_fma_f32 v[30:31], v[46:47], v[52:53], v[30:31]
	v_pk_fma_f32 v[22:23], v[40:41], v[26:27], v[22:23]
	v_pk_fma_f32 v[30:31], v[48:49], v[54:55], v[30:31]
	v_add_f32_e32 v19, v50, v22
	v_add_f32_e32 v19, v19, v23
	v_add_f32_e32 v19, v19, v30
	v_add_f32_e32 v19, v19, v31
	ds_read2_b32 v[20:21], v254 offset0:32 offset1:36
	ds_read2_b32 v[22:23], v254 offset0:33 offset1:37
	ds_read2_b32 v[24:25], v254 offset0:34 offset1:38
	ds_read2_b32 v[26:27], v254 offset0:35 offset1:39
	ds_read2_b32 v[28:29], v254 offset0:40 offset1:44
	ds_read2_b32 v[30:31], v254 offset0:41 offset1:45
	ds_read2_b32 v[52:53], v254 offset0:42 offset1:46
	ds_read2_b32 v[54:55], v254 offset0:43 offset1:47
	s_waitcnt lgkmcnt(8)
	v_min_f32_e32 v51, 0, v19
	v_pk_mul_f32 v[58:59], v[36:37], v[58:59]
	v_mul_f32_e64 v68, |v19|, s17
	v_pk_mul_f32 v[66:67], v[44:45], v[66:67]
	v_exp_f32_e32 v68, v68
	v_pk_fma_f32 v[58:59], v[34:35], v[56:57], v[58:59]
	v_pk_fma_f32 v[66:67], v[42:43], v[64:65], v[66:67]
	v_add_f32_e32 v68, 1.0, v68
	v_pk_fma_f32 v[58:59], v[38:39], v[60:61], v[58:59]
	v_log_f32_e32 v68, v68
	v_pk_fma_f32 v[66:67], v[46:47], v[214:215], v[66:67]
	v_pk_fma_f32 v[58:59], v[40:41], v[62:63], v[58:59]
	v_mul_f32_e32 v216, 0x3f317217, v68
	v_pk_fma_f32 v[66:67], v[48:49], v[252:253], v[66:67]
	v_fma_f32 v216, v68, s18, -v216
	v_add_f32_e32 v219, v50, v58
	v_fmac_f32_e32 v216, 0x3377d1cf, v68
	v_add_f32_e32 v219, v219, v59
	v_fmac_f32_e32 v216, 0x3f317217, v68
	v_add_f32_e32 v219, v219, v66
	v_sub_f32_e32 v51, v51, v216
	v_add_f32_e32 v219, v219, v67
	v_fmac_f32_e32 v16, 0x3d800000, v51
	ds_write_b32 v18, v16
	ds_read2_b32 v[56:57], v254 offset0:48 offset1:52
	ds_read2_b32 v[58:59], v254 offset0:49 offset1:53
	ds_read2_b32 v[60:61], v254 offset0:50 offset1:54
	ds_read2_b32 v[62:63], v254 offset0:51 offset1:55
	ds_read2_b32 v[64:65], v254 offset0:56 offset1:60
	ds_read2_b32 v[66:67], v254 offset0:57 offset1:61
	ds_read2_b32 v[214:215], v254 offset0:58 offset1:62
	ds_read2_b32 v[252:253], v254 offset0:59 offset1:63
	s_waitcnt lgkmcnt(8)
	v_min_f32_e32 v225, 0, v219
	v_pk_mul_f32 v[22:23], v[36:37], v[22:23]
	v_mul_f32_e64 v226, |v219|, s17
	v_pk_mul_f32 v[30:31], v[44:45], v[30:31]
	v_exp_f32_e32 v226, v226
	v_pk_fma_f32 v[22:23], v[34:35], v[20:21], v[22:23]
	v_pk_fma_f32 v[30:31], v[42:43], v[28:29], v[30:31]
	v_add_f32_e32 v226, 1.0, v226
	v_pk_fma_f32 v[22:23], v[38:39], v[24:25], v[22:23]
	v_log_f32_e32 v226, v226
	v_pk_fma_f32 v[30:31], v[46:47], v[52:53], v[30:31]
	v_pk_fma_f32 v[22:23], v[40:41], v[26:27], v[22:23]
	v_mul_f32_e32 v251, 0x3f317217, v226
	v_pk_fma_f32 v[30:31], v[48:49], v[54:55], v[30:31]
	v_fma_f32 v251, v226, s18, -v251
	v_add_f32_e32 v19, v50, v22
	v_fmac_f32_e32 v251, 0x3377d1cf, v226
	v_add_f32_e32 v19, v19, v23
	v_fmac_f32_e32 v251, 0x3f317217, v226
	v_add_f32_e32 v19, v19, v30
	v_sub_f32_e32 v225, v225, v251
	v_add_f32_e32 v19, v19, v31
	v_fmac_f32_e32 v16, 0x3d800000, v225
	ds_write_b32 v18, v16 offset:516
	s_waitcnt lgkmcnt(1)
	v_min_f32_e32 v51, 0, v19
	v_pk_mul_f32 v[58:59], v[36:37], v[58:59]
	v_mul_f32_e64 v68, |v19|, s17
	v_pk_mul_f32 v[66:67], v[44:45], v[66:67]
	v_exp_f32_e32 v68, v68
	v_pk_fma_f32 v[58:59], v[34:35], v[56:57], v[58:59]
	v_pk_fma_f32 v[66:67], v[42:43], v[64:65], v[66:67]
	v_add_f32_e32 v68, 1.0, v68
	v_pk_fma_f32 v[58:59], v[38:39], v[60:61], v[58:59]
	v_log_f32_e32 v68, v68
	v_pk_fma_f32 v[66:67], v[46:47], v[214:215], v[66:67]
	v_pk_fma_f32 v[58:59], v[40:41], v[62:63], v[58:59]
	v_mul_f32_e32 v216, 0x3f317217, v68
	v_pk_fma_f32 v[66:67], v[48:49], v[252:253], v[66:67]
	v_fma_f32 v216, v68, s18, -v216
	v_add_f32_e32 v219, v50, v58
	v_fmac_f32_e32 v216, 0x3377d1cf, v68
	v_add_f32_e32 v219, v219, v59
	v_fmac_f32_e32 v216, 0x3f317217, v68
	v_add_f32_e32 v219, v219, v66
	v_sub_f32_e32 v51, v51, v216
	v_add_f32_e32 v219, v219, v67
	v_fmac_f32_e32 v16, 0x3d800000, v51
	ds_write_b32 v18, v16 offset:1032
	v_min_f32_e32 v225, 0, v219
	v_mul_f32_e64 v226, |v219|, s17
	v_exp_f32_e32 v226, v226
	s_nop 0
	v_add_f32_e32 v226, 1.0, v226
	v_log_f32_e32 v226, v226
	s_nop 0
	v_mul_f32_e32 v251, 0x3f317217, v226
	v_fma_f32 v251, v226, s18, -v251
	v_fmac_f32_e32 v251, 0x3377d1cf, v226
	v_fmac_f32_e32 v251, 0x3f317217, v226
	v_sub_f32_e32 v225, v225, v251
	v_fmac_f32_e32 v16, 0x3d800000, v225
	ds_write_b32 v18, v16 offset:1548
	s_add_i32 s7, s7, -4
	v_add_u32_e32 v18, 0x810, v18
	v_add_u32_e32 v17, 0x100, v17
	s_cmp_eq_u32 s7, 0
	s_cbranch_scc0 .LBB0_352
	ds_write_b32 v122, v16
	s_waitcnt lgkmcnt(0)
	s_barrier
; __device__ __forceinline__ unsigned cvt_pk_bf16(float lo, float hi) { unsigned r; asm volatile("v_cvt_pk_bf16_f32 %0, %1, %2" : "=v"(r) : "v"(lo), "v"(hi)); return r; }
; #define LAS __attribute__((address_space(3)))
; __device__ __forceinline__ float bf_lo(unsigned w) { return __uint_as_float(w << 16); }
; __device__ __forceinline__ float bf_hi(unsigned w) { return __uint_as_float(w & 0xffff0000u); }
; __device__ __forceinline__ void gla_passA(LAS unsigned char* lds, int uidx, const bf16_t* PR, const float* GLRP, const float* w2, const float* gb,
;                                           bf16_t* SUB, float* EB, bf16_t* QT, bf16_t* AM, int tid, int wid, int lane) {
;     ...
;     {
;         const int j = tid >> 3, kr = (tid & 7) * 16, jg = j >> 4;
;         const float scale = 0.08838834764831845f;
;         u32x4 oq[2], ok[2], oh[2];
; #pragma unroll
;         for (int e4 = 0; e4 < 4; ++e4) {
;             const f32x4 t0 = *(const LAS f32x4*)(Tt + 0 * 128 + kr + 4 * e4), t1 = *(const LAS f32x4*)(Tt + 1 * 128 + kr + 4 * e4), t2 = *(const LAS f32x4*)(Tt + 2 * 128 + kr + 4 * e4), t3 = *(const LAS f32x4*)(Tt + 3 * 128 + kr + 4 * e4);
;             const f32x4 zz = {0.f, 0.f, 0.f, 0.f}; const f32x4 off = (jg > 0 ? t0 : zz) + (jg > 1 ? t1 : zz) + (jg > 2 ? t2 : zz), bc = (t0 + t1) + (t2 + t3);
; #pragma unroll
;             for (int eh = 0; eh < 2; ++eh) { const int e2 = 2 * e4 + eh; const unsigned qw = e2 < 4 ? qa[e2] : qb[e2 - 4], kw = e2 < 4 ? ka[e2] : kb[e2 - 4];
;                 const int k = kr + 2 * e2;
;                 const float b0 = Bc[j * 129 + k] + off[2 * eh], b1 = Bc[j * 129 + k + 1] + off[2 * eh + 1], c0 = bc[2 * eh], c1 = bc[2 * eh + 1];
;                 const float q0 = bf_lo(qw) * scale * __expf(b0), q1 = bf_hi(qw) * scale * __expf(b1);
;                 const float k0 = bf_lo(kw), k1 = bf_hi(kw);
;                 const unsigned pq = cvt_pk_bf16(q0, q1), pk = cvt_pk_bf16(k0 * __expf(-b0), k1 * __expf(-b1)), ph = cvt_pk_bf16(k0 * __expf(c0 - b0), k1 * __expf(c1 - b1));
;                 if (e2 < 4) { oq[0][e2] = pq; ok[0][e2] = pk; oh[0][e2] = ph; } else { oq[1][e2 - 4] = pq; ok[1][e2 - 4] = pk; oh[1][e2 - 4] = ph; } }
;         }
	ds_read_b128 v[16:19], v123
	ds_read_b128 v[20:23], v124
	ds_read_b128 v[24:27], v125
	ds_read_b128 v[28:31], v126
	s_lshl_b32 s10, s6, 1
	s_waitcnt lgkmcnt(3)
	v_cndmask_b32_e64 v35, 0, v19, s[44:45]
	v_cndmask_b32_e64 v34, 0, v18, s[44:45]
	v_cndmask_b32_e64 v37, 0, v17, s[44:45]
	v_cndmask_b32_e64 v36, 0, v16, s[44:45]
	s_waitcnt lgkmcnt(2)
	v_cndmask_b32_e64 v41, 0, v21, s[46:47]
	v_cndmask_b32_e64 v40, 0, v20, s[46:47]
	v_pk_add_f32 v[18:19], v[18:19], v[22:23]
	v_pk_add_f32 v[16:17], v[16:17], v[20:21]
	s_waitcnt lgkmcnt(0)
	v_pk_add_f32 v[20:21], v[26:27], v[30:31]
	v_cndmask_b32_e64 v39, 0, v23, s[46:47]
	v_pk_add_f32 v[18:19], v[18:19], v[20:21]
	ds_read2_b32 v[20:21], v127 offset1:1
	v_cndmask_b32_e64 v38, 0, v22, s[46:47]
	v_pk_add_f32 v[36:37], v[36:37], v[40:41]
	v_pk_add_f32 v[34:35], v[34:35], v[38:39]
	v_cndmask_b32_e64 v39, 0, v25, s[48:49]
	v_cndmask_b32_e64 v38, 0, v24, s[48:49]
	v_pk_add_f32 v[36:37], v[36:37], v[38:39]
	v_pk_add_f32 v[22:23], v[24:25], v[28:29]
	s_waitcnt lgkmcnt(0)
	v_add_f32_e32 v20, v20, v36
	v_pk_add_f32 v[16:17], v[16:17], v[22:23]
	v_mul_f32_e32 v23, 0x3fb8aa3b, v20
	v_exp_f32_e32 v23, v23
	v_lshlrev_b32_e32 v22, 16, v12
	v_add_f32_e32 v21, v37, v21
	v_mul_f32_e32 v22, 0x3db504f3, v22
	v_mul_f32_e32 v22, v22, v23
	v_mul_f32_e32 v23, 0x3fb8aa3b, v21
	v_exp_f32_e32 v23, v23
	v_and_b32_e32 v12, 0xffff0000, v12
	v_mul_f32_e32 v12, 0x3db504f3, v12
	v_sub_f32_e32 v16, v16, v20
	v_mul_f32_e32 v12, v12, v23
	v_lshlrev_b32_e32 v23, 16, v8
	v_and_b32_e32 v24, 0xffff0000, v8
	v_cvt_pk_bf16_f32 v8, v22, v12
	v_mul_f32_e32 v12, 0xbfb8aa3b, v20
	v_mul_f32_e32 v16, 0x3fb8aa3b, v16
	v_sub_f32_e32 v17, v17, v21
	v_exp_f32_e32 v12, v12
	v_mul_f32_e32 v22, 0xbfb8aa3b, v21
	v_exp_f32_e32 v16, v16
	v_mul_f32_e32 v17, 0x3fb8aa3b, v17
	v_exp_f32_e32 v22, v22
	v_exp_f32_e32 v17, v17
	v_mul_f32_e32 v12, v12, v23
	v_mul_f32_e32 v16, v16, v23
	v_mul_f32_e32 v22, v22, v24
	v_cvt_pk_bf16_f32 v12, v12, v22
	v_mul_f32_e32 v17, v17, v24
	v_cvt_pk_bf16_f32 v16, v16, v17
	ds_read2_b32 v[20:21], v127 offset0:2 offset1:3
	v_cndmask_b32_e64 v41, 0, v27, s[48:49]
	v_cndmask_b32_e64 v40, 0, v26, s[48:49]
	v_pk_add_f32 v[34:35], v[34:35], v[40:41]
	v_and_b32_e32 v23, 0xffff0000, v9
	s_waitcnt lgkmcnt(0)
	v_add_f32_e32 v17, v34, v20
	v_mul_f32_e32 v22, 0x3fb8aa3b, v17
	v_exp_f32_e32 v22, v22
	v_add_f32_e32 v20, v35, v21
	v_lshlrev_b32_e32 v21, 16, v13
	v_mul_f32_e32 v21, 0x3db504f3, v21
	v_mul_f32_e32 v21, v21, v22
	v_mul_f32_e32 v22, 0x3fb8aa3b, v20
	v_exp_f32_e32 v22, v22
	v_and_b32_e32 v13, 0xffff0000, v13
	v_mul_f32_e32 v13, 0x3db504f3, v13
	s_lshl_b32 s7, s67, 2
	v_mul_f32_e32 v13, v13, v22
	v_lshlrev_b32_e32 v22, 16, v9
	v_cvt_pk_bf16_f32 v9, v21, v13
	v_mul_f32_e32 v13, 0xbfb8aa3b, v17
	v_sub_f32_e32 v17, v18, v17
	v_sub_f32_e32 v18, v19, v20
	v_mul_f32_e32 v21, 0xbfb8aa3b, v20
	v_mul_f32_e32 v17, 0x3fb8aa3b, v17
	v_mul_f32_e32 v18, 0x3fb8aa3b, v18
	v_exp_f32_e32 v13, v13
	v_exp_f32_e32 v21, v21
	v_exp_f32_e32 v17, v17
	v_exp_f32_e32 v18, v18
	v_mul_f32_e32 v13, v13, v22
	v_mul_f32_e32 v21, v21, v23
	v_mul_f32_e32 v17, v17, v22
	v_mul_f32_e32 v18, v18, v23
	v_cvt_pk_bf16_f32 v13, v13, v21
	v_cvt_pk_bf16_f32 v17, v17, v18
	ds_read_b128 v[18:21], v123 offset:16
	ds_read_b128 v[22:25], v124 offset:16
	ds_read_b128 v[26:29], v125 offset:16
	ds_read_b128 v[34:37], v126 offset:16
	s_or_b32 s86, s7, s68
	s_waitcnt lgkmcnt(3)
	v_cndmask_b32_e64 v31, 0, v21, s[44:45]
	v_cndmask_b32_e64 v30, 0, v20, s[44:45]
	v_cndmask_b32_e64 v39, 0, v19, s[44:45]
	v_cndmask_b32_e64 v38, 0, v18, s[44:45]
	s_waitcnt lgkmcnt(2)
	v_cndmask_b32_e64 v43, 0, v23, s[46:47]
	v_cndmask_b32_e64 v42, 0, v22, s[46:47]
	v_pk_add_f32 v[20:21], v[20:21], v[24:25]
	v_pk_add_f32 v[18:19], v[18:19], v[22:23]
	s_waitcnt lgkmcnt(0)
	v_pk_add_f32 v[22:23], v[28:29], v[36:37]
	v_cndmask_b32_e64 v41, 0, v25, s[46:47]
	v_pk_add_f32 v[20:21], v[20:21], v[22:23]
	ds_read2_b32 v[22:23], v127 offset0:4 offset1:5
	v_cndmask_b32_e64 v40, 0, v24, s[46:47]
	v_pk_add_f32 v[38:39], v[38:39], v[42:43]
	v_pk_add_f32 v[30:31], v[30:31], v[40:41]
	v_cndmask_b32_e64 v41, 0, v27, s[48:49]
	v_cndmask_b32_e64 v40, 0, v26, s[48:49]
	v_pk_add_f32 v[38:39], v[38:39], v[40:41]
	v_pk_add_f32 v[24:25], v[26:27], v[34:35]
	s_waitcnt lgkmcnt(0)
	v_add_f32_e32 v22, v22, v38
	v_pk_add_f32 v[18:19], v[18:19], v[24:25]
	v_mul_f32_e32 v25, 0x3fb8aa3b, v22
	v_exp_f32_e32 v25, v25
	v_lshlrev_b32_e32 v24, 16, v14
	v_add_f32_e32 v23, v39, v23
	v_mul_f32_e32 v24, 0x3db504f3, v24
	v_mul_f32_e32 v24, v24, v25
	v_mul_f32_e32 v25, 0x3fb8aa3b, v23
	v_exp_f32_e32 v25, v25
	v_and_b32_e32 v14, 0xffff0000, v14
	v_mul_f32_e32 v14, 0x3db504f3, v14
	v_sub_f32_e32 v18, v18, v22
	v_mul_f32_e32 v14, v14, v25
	v_lshlrev_b32_e32 v25, 16, v10
	v_and_b32_e32 v26, 0xffff0000, v10
	v_cvt_pk_bf16_f32 v10, v24, v14
	v_mul_f32_e32 v14, 0xbfb8aa3b, v22
	v_mul_f32_e32 v18, 0x3fb8aa3b, v18
	v_sub_f32_e32 v19, v19, v23
	v_exp_f32_e32 v14, v14
	v_mul_f32_e32 v24, 0xbfb8aa3b, v23
	v_exp_f32_e32 v18, v18
	v_mul_f32_e32 v19, 0x3fb8aa3b, v19
	v_exp_f32_e32 v24, v24
	v_exp_f32_e32 v19, v19
	v_mul_f32_e32 v14, v14, v25
	v_mul_f32_e32 v18, v18, v25
	v_mul_f32_e32 v24, v24, v26
	v_cvt_pk_bf16_f32 v14, v14, v24
	v_mul_f32_e32 v19, v19, v26
	v_cvt_pk_bf16_f32 v18, v18, v19
	ds_read2_b32 v[22:23], v127 offset0:6 offset1:7
	v_cndmask_b32_e64 v43, 0, v29, s[48:49]
	v_cndmask_b32_e64 v42, 0, v28, s[48:49]
	v_pk_add_f32 v[30:31], v[30:31], v[42:43]
	v_and_b32_e32 v25, 0xffff0000, v11
	s_waitcnt lgkmcnt(0)
; __device__ __forceinline__ unsigned cvt_pk_bf16(float lo, float hi) { unsigned r; asm volatile("v_cvt_pk_bf16_f32 %0, %1, %2" : "=v"(r) : "v"(lo), "v"(hi)); return r; }
; #define LAS __attribute__((address_space(3)))
; __device__ __forceinline__ float bf_lo(unsigned w) { return __uint_as_float(w << 16); }
; __device__ __forceinline__ float bf_hi(unsigned w) { return __uint_as_float(w & 0xffff0000u); }
; __device__ __forceinline__ void gla_passA(LAS unsigned char* lds, int uidx, const bf16_t* PR, const float* GLRP, const float* w2, const float* gb,
;                                           bf16_t* SUB, float* EB, bf16_t* QT, bf16_t* AM, int tid, int wid, int lane) {
;     ...
;         for (int e4 = 0; e4 < 4; ++e4) {
;             const f32x4 t0 = *(const LAS f32x4*)(Tt + 0 * 128 + kr + 4 * e4), t1 = *(const LAS f32x4*)(Tt + 1 * 128 + kr + 4 * e4), t2 = *(const LAS f32x4*)(Tt + 2 * 128 + kr + 4 * e4), t3 = *(const LAS f32x4*)(Tt + 3 * 128 + kr + 4 * e4);
;             const f32x4 zz = {0.f, 0.f, 0.f, 0.f}; const f32x4 off = (jg > 0 ? t0 : zz) + (jg > 1 ? t1 : zz) + (jg > 2 ? t2 : zz), bc = (t0 + t1) + (t2 + t3);
; #pragma unroll
;             for (int eh = 0; eh < 2; ++eh) { const int e2 = 2 * e4 + eh; const unsigned qw = e2 < 4 ? qa[e2] : qb[e2 - 4], kw = e2 < 4 ? ka[e2] : kb[e2 - 4];
;                 const int k = kr + 2 * e2;
;                 const float b0 = Bc[j * 129 + k] + off[2 * eh], b1 = Bc[j * 129 + k + 1] + off[2 * eh + 1], c0 = bc[2 * eh], c1 = bc[2 * eh + 1];
;                 const float q0 = bf_lo(qw) * scale * __expf(b0), q1 = bf_hi(qw) * scale * __expf(b1);
;                 const float k0 = bf_lo(kw), k1 = bf_hi(kw);
;                 const unsigned pq = cvt_pk_bf16(q0, q1), pk = cvt_pk_bf16(k0 * __expf(-b0), k1 * __expf(-b1)), ph = cvt_pk_bf16(k0 * __expf(c0 - b0), k1 * __expf(c1 - b1));
;                 if (e2 < 4) { oq[0][e2] = pq; ok[0][e2] = pk; oh[0][e2] = ph; } else { oq[1][e2 - 4] = pq; ok[1][e2 - 4] = pk; oh[1][e2 - 4] = ph; } }
;         }
	v_add_f32_e32 v19, v30, v22
	v_mul_f32_e32 v24, 0x3fb8aa3b, v19
	v_exp_f32_e32 v24, v24
	v_add_f32_e32 v22, v31, v23
	v_lshlrev_b32_e32 v23, 16, v15
	v_mul_f32_e32 v23, 0x3db504f3, v23
	v_mul_f32_e32 v23, v23, v24
	v_mul_f32_e32 v24, 0x3fb8aa3b, v22
	v_exp_f32_e32 v24, v24
	v_and_b32_e32 v15, 0xffff0000, v15
	v_mul_f32_e32 v15, 0x3db504f3, v15
	v_mul_f32_e32 v15, v15, v24
	v_lshlrev_b32_e32 v24, 16, v11
	v_cvt_pk_bf16_f32 v11, v23, v15
	v_mul_f32_e32 v15, 0xbfb8aa3b, v19
	v_sub_f32_e32 v19, v20, v19
	v_sub_f32_e32 v20, v21, v22
	v_mul_f32_e32 v23, 0xbfb8aa3b, v22
	v_mul_f32_e32 v19, 0x3fb8aa3b, v19
	v_mul_f32_e32 v20, 0x3fb8aa3b, v20
	v_exp_f32_e32 v15, v15
	v_exp_f32_e32 v23, v23
	v_exp_f32_e32 v19, v19
	v_exp_f32_e32 v20, v20
	v_mul_f32_e32 v15, v15, v24
	v_mul_f32_e32 v23, v23, v25
	v_mul_f32_e32 v19, v19, v24
	v_mul_f32_e32 v20, v20, v25
	v_cvt_pk_bf16_f32 v15, v15, v23
	v_cvt_pk_bf16_f32 v19, v19, v20
	ds_read_b128 v[20:23], v123 offset:32
	ds_read_b128 v[24:27], v124 offset:32
	ds_read_b128 v[28:31], v125 offset:32
	ds_read_b128 v[34:37], v126 offset:32
	s_waitcnt lgkmcnt(3)
	v_cndmask_b32_e64 v39, 0, v23, s[44:45]
	v_cndmask_b32_e64 v38, 0, v22, s[44:45]
	v_cndmask_b32_e64 v41, 0, v21, s[44:45]
	v_cndmask_b32_e64 v40, 0, v20, s[44:45]
	s_waitcnt lgkmcnt(2)
	v_cndmask_b32_e64 v45, 0, v25, s[46:47]
	v_cndmask_b32_e64 v44, 0, v24, s[46:47]
	v_pk_add_f32 v[22:23], v[22:23], v[26:27]
	v_pk_add_f32 v[20:21], v[20:21], v[24:25]
	s_waitcnt lgkmcnt(0)
	v_pk_add_f32 v[24:25], v[30:31], v[36:37]
	v_cndmask_b32_e64 v43, 0, v27, s[46:47]
	v_pk_add_f32 v[22:23], v[22:23], v[24:25]
	ds_read2_b32 v[24:25], v127 offset0:8 offset1:9
	v_cndmask_b32_e64 v42, 0, v26, s[46:47]
	v_pk_add_f32 v[40:41], v[40:41], v[44:45]
	v_pk_add_f32 v[38:39], v[38:39], v[42:43]
	v_cndmask_b32_e64 v43, 0, v29, s[48:49]
	v_cndmask_b32_e64 v42, 0, v28, s[48:49]
	v_pk_add_f32 v[40:41], v[40:41], v[42:43]
	v_pk_add_f32 v[26:27], v[28:29], v[34:35]
	s_waitcnt lgkmcnt(0)
	v_add_f32_e32 v24, v24, v40
	v_pk_add_f32 v[20:21], v[20:21], v[26:27]
	v_mul_f32_e32 v27, 0x3fb8aa3b, v24
	v_exp_f32_e32 v27, v27
	v_lshlrev_b32_e32 v26, 16, v4
	v_add_f32_e32 v25, v41, v25
	v_mul_f32_e32 v26, 0x3db504f3, v26
	v_mul_f32_e32 v26, v26, v27
	v_mul_f32_e32 v27, 0x3fb8aa3b, v25
	v_exp_f32_e32 v27, v27
	v_and_b32_e32 v4, 0xffff0000, v4
	v_mul_f32_e32 v4, 0x3db504f3, v4
	v_sub_f32_e32 v20, v20, v24
	v_mul_f32_e32 v4, v4, v27
	v_lshlrev_b32_e32 v27, 16, v0
	v_and_b32_e32 v28, 0xffff0000, v0
	v_cvt_pk_bf16_f32 v0, v26, v4
	v_mul_f32_e32 v4, 0xbfb8aa3b, v24
	v_mul_f32_e32 v20, 0x3fb8aa3b, v20
	v_sub_f32_e32 v21, v21, v25
	v_exp_f32_e32 v4, v4
	v_mul_f32_e32 v26, 0xbfb8aa3b, v25
	v_exp_f32_e32 v20, v20
	v_mul_f32_e32 v21, 0x3fb8aa3b, v21
	v_exp_f32_e32 v26, v26
	v_exp_f32_e32 v21, v21
	v_mul_f32_e32 v4, v4, v27
	v_mul_f32_e32 v20, v20, v27
	v_mul_f32_e32 v26, v26, v28
	v_cvt_pk_bf16_f32 v4, v4, v26
	v_mul_f32_e32 v21, v21, v28
	v_cvt_pk_bf16_f32 v20, v20, v21
	ds_read2_b32 v[24:25], v127 offset0:10 offset1:11
	v_cndmask_b32_e64 v45, 0, v31, s[48:49]
	v_cndmask_b32_e64 v44, 0, v30, s[48:49]
	v_pk_add_f32 v[38:39], v[38:39], v[44:45]
	v_and_b32_e32 v27, 0xffff0000, v1
	s_waitcnt lgkmcnt(0)
	v_add_f32_e32 v21, v38, v24
	v_mul_f32_e32 v26, 0x3fb8aa3b, v21
	v_exp_f32_e32 v26, v26
	v_add_f32_e32 v24, v39, v25
	v_lshlrev_b32_e32 v25, 16, v5
	v_mul_f32_e32 v25, 0x3db504f3, v25
	v_mul_f32_e32 v25, v25, v26
	v_mul_f32_e32 v26, 0x3fb8aa3b, v24
	v_exp_f32_e32 v26, v26
	v_and_b32_e32 v5, 0xffff0000, v5
	v_mul_f32_e32 v5, 0x3db504f3, v5
	v_mul_f32_e32 v5, v5, v26
	v_lshlrev_b32_e32 v26, 16, v1
	v_cvt_pk_bf16_f32 v1, v25, v5
	v_mul_f32_e32 v5, 0xbfb8aa3b, v21
	v_sub_f32_e32 v21, v22, v21
	v_sub_f32_e32 v22, v23, v24
	v_mul_f32_e32 v25, 0xbfb8aa3b, v24
	v_mul_f32_e32 v21, 0x3fb8aa3b, v21
	v_mul_f32_e32 v22, 0x3fb8aa3b, v22
	v_exp_f32_e32 v5, v5
	v_exp_f32_e32 v25, v25
	v_exp_f32_e32 v21, v21
	v_exp_f32_e32 v22, v22
	v_mul_f32_e32 v5, v5, v26
	v_mul_f32_e32 v25, v25, v27
	v_mul_f32_e32 v21, v21, v26
	v_mul_f32_e32 v22, v22, v27
	v_cvt_pk_bf16_f32 v5, v5, v25
	v_cvt_pk_bf16_f32 v21, v21, v22
	ds_read_b128 v[22:25], v123 offset:48
	ds_read_b128 v[26:29], v124 offset:48
	ds_read_b128 v[34:37], v125 offset:48
	ds_read_b128 v[38:41], v126 offset:48
	s_waitcnt lgkmcnt(3)
; __device__ __forceinline__ unsigned cvt_pk_bf16(float lo, float hi) { unsigned r; asm volatile("v_cvt_pk_bf16_f32 %0, %1, %2" : "=v"(r) : "v"(lo), "v"(hi)); return r; }
; #define LAS __attribute__((address_space(3)))
; __device__ __forceinline__ void gla_passA(LAS unsigned char* lds, int uidx, const bf16_t* PR, const float* GLRP, const float* w2, const float* gb,
;                                           bf16_t* SUB, float* EB, bf16_t* QT, bf16_t* AM, int tid, int wid, int lane) {
;     ...
;         for (int e4 = 0; e4 < 4; ++e4) {
;             const f32x4 t0 = *(const LAS f32x4*)(Tt + 0 * 128 + kr + 4 * e4), t1 = *(const LAS f32x4*)(Tt + 1 * 128 + kr + 4 * e4), t2 = *(const LAS f32x4*)(Tt + 2 * 128 + kr + 4 * e4), t3 = *(const LAS f32x4*)(Tt + 3 * 128 + kr + 4 * e4);
;             const f32x4 zz = {0.f, 0.f, 0.f, 0.f}; const f32x4 off = (jg > 0 ? t0 : zz) + (jg > 1 ? t1 : zz) + (jg > 2 ? t2 : zz), bc = (t0 + t1) + (t2 + t3);
; #pragma unroll
;             for (int eh = 0; eh < 2; ++eh) { const int e2 = 2 * e4 + eh; const unsigned qw = e2 < 4 ? qa[e2] : qb[e2 - 4], kw = e2 < 4 ? ka[e2] : kb[e2 - 4];
;                 const int k = kr + 2 * e2;
;                 const float b0 = Bc[j * 129 + k] + off[2 * eh], b1 = Bc[j * 129 + k + 1] + off[2 * eh + 1], c0 = bc[2 * eh], c1 = bc[2 * eh + 1];
;                 const float q0 = bf_lo(qw) * scale * __expf(b0), q1 = bf_hi(qw) * scale * __expf(b1);
;                 const float k0 = bf_lo(kw), k1 = bf_hi(kw);
;                 const unsigned pq = cvt_pk_bf16(q0, q1), pk = cvt_pk_bf16(k0 * __expf(-b0), k1 * __expf(-b1)), ph = cvt_pk_bf16(k0 * __expf(c0 - b0), k1 * __expf(c1 - b1));
;                 if (e2 < 4) { oq[0][e2] = pq; ok[0][e2] = pk; oh[0][e2] = ph; } else { oq[1][e2 - 4] = pq; ok[1][e2 - 4] = pk; oh[1][e2 - 4] = ph; } }
;         }
;         *(LAS u32x4*)(Qs + j * 136 + kr) = oq[0]; *(LAS u32x4*)(Qs + j * 136 + kr + 8) = oq[1];
;         *(LAS u32x4*)(Ks + j * 136 + kr) = ok[0]; *(LAS u32x4*)(Ks + j * 136 + kr + 8) = ok[1];
;         *(LAS u32x4*)(Kh + j * 136 + kr) = oh[0]; *(LAS u32x4*)(Kh + j * 136 + kr + 8) = oh[1];
;         bf16_t* qt = QT + (size_t)(tok0 + j) * QKD + h * DK + kr; *(u32x4*)qt = oq[0]; *(u32x4*)(qt + 8) = oq[1];
;         if (tid < DK) EB[((size_t)bh * NCH + c) * DK + tid] = __expf((Tt[tid] + Tt[128 + tid]) + (Tt[256 + tid] + Tt[384 + tid]));
;     }
	v_cndmask_b32_e64 v31, 0, v25, s[44:45]
	v_cndmask_b32_e64 v30, 0, v24, s[44:45]
	v_cndmask_b32_e64 v43, 0, v23, s[44:45]
	v_cndmask_b32_e64 v42, 0, v22, s[44:45]
	s_waitcnt lgkmcnt(2)
	v_cndmask_b32_e64 v47, 0, v27, s[46:47]
	v_cndmask_b32_e64 v46, 0, v26, s[46:47]
	v_pk_add_f32 v[24:25], v[24:25], v[28:29]
	v_pk_add_f32 v[22:23], v[22:23], v[26:27]
	s_waitcnt lgkmcnt(0)
	v_pk_add_f32 v[26:27], v[36:37], v[40:41]
	v_cndmask_b32_e64 v45, 0, v29, s[46:47]
	v_pk_add_f32 v[24:25], v[24:25], v[26:27]
	ds_read2_b32 v[26:27], v127 offset0:12 offset1:13
	v_cndmask_b32_e64 v44, 0, v28, s[46:47]
	v_pk_add_f32 v[42:43], v[42:43], v[46:47]
	v_pk_add_f32 v[30:31], v[30:31], v[44:45]
	v_cndmask_b32_e64 v45, 0, v35, s[48:49]
	v_cndmask_b32_e64 v44, 0, v34, s[48:49]
	v_pk_add_f32 v[42:43], v[42:43], v[44:45]
	v_pk_add_f32 v[28:29], v[34:35], v[38:39]
	s_waitcnt lgkmcnt(0)
	v_add_f32_e32 v26, v26, v42
	v_pk_add_f32 v[22:23], v[22:23], v[28:29]
	v_mul_f32_e32 v29, 0x3fb8aa3b, v26
	v_exp_f32_e32 v29, v29
	v_lshlrev_b32_e32 v28, 16, v6
	v_add_f32_e32 v27, v43, v27
	v_mul_f32_e32 v28, 0x3db504f3, v28
	v_mul_f32_e32 v28, v28, v29
	v_mul_f32_e32 v29, 0x3fb8aa3b, v27
	v_exp_f32_e32 v29, v29
	v_and_b32_e32 v6, 0xffff0000, v6
	v_mul_f32_e32 v6, 0x3db504f3, v6
	v_sub_f32_e32 v22, v22, v26
	v_mul_f32_e32 v6, v6, v29
	v_lshlrev_b32_e32 v29, 16, v2
	v_and_b32_e32 v34, 0xffff0000, v2
	v_cvt_pk_bf16_f32 v2, v28, v6
	v_mul_f32_e32 v6, 0xbfb8aa3b, v26
	v_mul_f32_e32 v22, 0x3fb8aa3b, v22
	v_sub_f32_e32 v23, v23, v27
	v_exp_f32_e32 v6, v6
	v_mul_f32_e32 v28, 0xbfb8aa3b, v27
	v_exp_f32_e32 v22, v22
	v_mul_f32_e32 v23, 0x3fb8aa3b, v23
	v_exp_f32_e32 v28, v28
	v_exp_f32_e32 v23, v23
	v_mul_f32_e32 v6, v6, v29
	v_mul_f32_e32 v22, v22, v29
	v_mul_f32_e32 v28, v28, v34
	v_cvt_pk_bf16_f32 v6, v6, v28
	v_mul_f32_e32 v23, v23, v34
	v_cvt_pk_bf16_f32 v22, v22, v23
	ds_read2_b32 v[26:27], v127 offset0:14 offset1:15
	v_cndmask_b32_e64 v47, 0, v37, s[48:49]
	v_cndmask_b32_e64 v46, 0, v36, s[48:49]
	v_pk_add_f32 v[30:31], v[30:31], v[46:47]
	v_and_b32_e32 v29, 0xffff0000, v3
	s_waitcnt lgkmcnt(0)
	v_add_f32_e32 v23, v30, v26
	v_mul_f32_e32 v28, 0x3fb8aa3b, v23
	v_exp_f32_e32 v28, v28
	v_add_f32_e32 v26, v31, v27
	v_lshlrev_b32_e32 v27, 16, v7
	v_mul_f32_e32 v27, 0x3db504f3, v27
	v_mul_f32_e32 v27, v27, v28
	v_mul_f32_e32 v28, 0x3fb8aa3b, v26
	v_exp_f32_e32 v28, v28
	v_and_b32_e32 v7, 0xffff0000, v7
	v_mul_f32_e32 v7, 0x3db504f3, v7
	v_mul_f32_e32 v7, v7, v28
	v_lshlrev_b32_e32 v28, 16, v3
	v_cvt_pk_bf16_f32 v3, v27, v7
	v_mul_f32_e32 v7, 0xbfb8aa3b, v23
	v_sub_f32_e32 v23, v24, v23
	v_mul_f32_e32 v23, 0x3fb8aa3b, v23
	v_sub_f32_e32 v24, v25, v26
	v_exp_f32_e32 v7, v7
	v_mul_f32_e32 v27, 0xbfb8aa3b, v26
	v_exp_f32_e32 v23, v23
	v_mul_f32_e32 v24, 0x3fb8aa3b, v24
	v_exp_f32_e32 v27, v27
	v_exp_f32_e32 v24, v24
	v_mul_f32_e32 v7, v7, v28
	v_mul_f32_e32 v23, v23, v28
	v_mul_f32_e32 v27, v27, v29
	v_cvt_pk_bf16_f32 v7, v7, v27
	v_mul_f32_e32 v24, v24, v29
	v_cvt_pk_bf16_f32 v23, v23, v24
	ds_write_b128 v128, v[8:11] offset:33536
	ds_write_b128 v128, v[0:3] offset:33552
	ds_write_b128 v128, v[12:15] offset:50944
	ds_write_b128 v128, v[4:7] offset:50960
	ds_write_b128 v129, v[16:19]
	ds_write_b128 v129, v[20:23] offset:16
	v_lshlrev_b64 v[4:5], 10, v[32:33]
	v_lshl_add_u64 v[4:5], s[34:35], 0, v[4:5]
	v_lshl_add_u64 v[4:5], v[4:5], 0, s[10:11]
	v_lshl_add_u64 v[4:5], v[4:5], 0, v[168:169]
	global_store_dwordx4 v[4:5], v[8:11], off
	global_store_dwordx4 v[4:5], v[0:3], off offset:16
	s_and_saveexec_b64 s[6:7], s[42:43]
	s_xor_b64 s[6:7], exec, s[6:7]
	s_ashr_i32 s87, s86, 31
	s_or_saveexec_b64 s[6:7], s[6:7]
	v_mov_b64_e32 v[108:109], s[86:87]
	s_xor_b64 exec, exec, s[6:7]
	s_cbranch_execz .LBB0_348
	ds_read2st64_b32 v[0:1], v122 offset1:2
	ds_read2st64_b32 v[2:3], v122 offset0:4 offset1:6
	s_ashr_i32 s87, s86, 31
	s_lshl_b64 s[68:69], s[86:87], 14
	s_add_u32 s10, s9, s68
	s_waitcnt lgkmcnt(1)
	v_mov_b32_e32 v4, v0
	s_waitcnt lgkmcnt(0)
	v_mov_b32_e32 v5, v2
	v_mov_b32_e32 v2, v1
	v_pk_add_f32 v[0:1], v[4:5], v[2:3]
	s_addc_u32 s67, s30, s69
	v_add_f32_e32 v0, v0, v1
	v_mul_f32_e32 v0, 0x3fb8aa3b, v0
	v_exp_f32_e32 v2, v0
	s_lshl_b32 s68, s31, 9
	s_add_u32 s68, s10, s68
	s_addc_u32 s69, s67, 0
	v_lshl_add_u64 v[0:1], v[112:113], 2, s[68:69]
	v_mov_b64_e32 v[108:109], s[86:87]
	global_store_dword v[0:1], v2, off
	s_branch .LBB0_348
